# stack: next-row touch prefetch for the norm1 sample rows + second-half touch in the fp16 residual epilogues + setprio pair trimming
# baseline (speedup 1.0000x reference)
.LBB0_321:
	v_lshl_add_u64 v[212:213], v[26:27], 0, s[82:83]
	v_add_co_u32_e32 v214, vcc, 0xe5b00000, v212
	s_nop 1
	v_addc_co_u32_e32 v215, vcc, -1, v213, vcc
	global_load_dword v216, v[214:215], off
	global_load_dword v216, v[212:213], off
	v_add_co_u32_e32 v214, vcc, 0x200000, v212
	s_nop 1
	v_addc_co_u32_e32 v215, vcc, 0, v213, vcc
	global_load_dword v216, v[214:215], off
	v_add_co_u32_e32 v214, vcc, 0x400000, v212
	s_nop 1
	v_addc_co_u32_e32 v215, vcc, 0, v213, vcc
	global_load_dword v216, v[214:215], off
	v_add_co_u32_e32 v214, vcc, 0x600000, v212
	s_nop 1
	v_addc_co_u32_e32 v215, vcc, 0, v213, vcc
	global_load_dword v216, v[214:215], off
	v_add_co_u32_e32 v214, vcc, 0x800000, v212
	s_nop 1
	v_addc_co_u32_e32 v215, vcc, 0, v213, vcc
	global_load_dword v216, v[214:215], off
	v_add_co_u32_e32 v214, vcc, 0xa00000, v212
	s_nop 1
	v_addc_co_u32_e32 v215, vcc, 0, v213, vcc
	global_load_dword v216, v[214:215], off
	v_add_co_u32_e32 v214, vcc, 0xc00000, v212
	s_nop 1
	v_addc_co_u32_e32 v215, vcc, 0, v213, vcc
	global_load_dword v216, v[214:215], off
	v_add_co_u32_e32 v214, vcc, 0xe00000, v212
	s_nop 1
	v_addc_co_u32_e32 v215, vcc, 0, v213, vcc
	global_load_dword v216, v[214:215], off
	v_add_co_u32_e32 v214, vcc, 0x1000000, v212
	s_nop 1
	v_addc_co_u32_e32 v215, vcc, 0, v213, vcc
	global_load_dword v216, v[214:215], off
	v_add_co_u32_e32 v214, vcc, 0x1200000, v212
	s_nop 1
	v_addc_co_u32_e32 v215, vcc, 0, v213, vcc
	global_load_dword v216, v[214:215], off
	v_add_co_u32_e32 v214, vcc, 0x1400000, v212
	s_nop 1
	v_addc_co_u32_e32 v215, vcc, 0, v213, vcc
	global_load_dword v216, v[214:215], off
	v_add_co_u32_e32 v214, vcc, 0x1600000, v212
	s_nop 1
	v_addc_co_u32_e32 v215, vcc, 0, v213, vcc
	global_load_dword v216, v[214:215], off
	v_add_co_u32_e32 v214, vcc, 0x1800000, v212
	s_nop 1
	v_addc_co_u32_e32 v215, vcc, 0, v213, vcc
	global_load_dword v216, v[214:215], off
	v_add_co_u32_e32 v214, vcc, 0x1a00000, v212
	s_nop 1
	v_addc_co_u32_e32 v215, vcc, 0, v213, vcc
	global_load_dword v216, v[214:215], off
	v_add_co_u32_e32 v214, vcc, 0x1c00000, v212
	s_nop 1
	v_addc_co_u32_e32 v215, vcc, 0, v213, vcc
	global_load_dword v216, v[214:215], off
	v_add_co_u32_e32 v214, vcc, 0x1e00000, v212
	s_nop 1
	v_addc_co_u32_e32 v215, vcc, 0, v213, vcc
	global_load_dword v216, v[214:215], off
	v_add_co_u32_e32 v184, vcc, 0x400000, v26
	s_nop 1
	v_addc_co_u32_e32 v185, vcc, 0, v27, vcc
	global_load_dwordx2 v[184:185], v[184:185], off
	v_add_co_u32_e32 v186, vcc, 0x600000, v26
	s_nop 1
	v_addc_co_u32_e32 v187, vcc, 0, v27, vcc
	global_load_dwordx2 v[186:187], v[186:187], off
	v_add_co_u32_e32 v188, vcc, 0x800000, v26
	s_nop 1
	v_addc_co_u32_e32 v189, vcc, 0, v27, vcc
	global_load_dwordx2 v[188:189], v[188:189], off
	v_add_co_u32_e32 v190, vcc, 0xa00000, v26
	s_nop 1
	v_addc_co_u32_e32 v191, vcc, 0, v27, vcc
	global_load_dwordx2 v[190:191], v[190:191], off
	v_add_co_u32_e32 v192, vcc, 0xc00000, v26
	s_nop 1
	v_addc_co_u32_e32 v193, vcc, 0, v27, vcc
	global_load_dwordx2 v[192:193], v[192:193], off
	v_add_co_u32_e32 v194, vcc, 0xe00000, v26
	s_nop 1
	v_addc_co_u32_e32 v195, vcc, 0, v27, vcc
	global_load_dwordx2 v[194:195], v[194:195], off
	v_add_co_u32_e32 v196, vcc, 0x1000000, v26
	s_nop 1
	v_addc_co_u32_e32 v197, vcc, 0, v27, vcc
	global_load_dwordx2 v[196:197], v[196:197], off
	v_add_co_u32_e32 v198, vcc, 0x1200000, v26
	s_nop 1
	v_addc_co_u32_e32 v199, vcc, 0, v27, vcc
	global_load_dwordx2 v[198:199], v[198:199], off
	v_add_co_u32_e32 v200, vcc, 0x1400000, v26
	s_nop 1
	v_addc_co_u32_e32 v201, vcc, 0, v27, vcc
	global_load_dwordx2 v[200:201], v[200:201], off
	v_add_co_u32_e32 v202, vcc, 0x1600000, v26
	s_nop 1
	v_addc_co_u32_e32 v203, vcc, 0, v27, vcc
	global_load_dwordx2 v[202:203], v[202:203], off
	v_add_co_u32_e32 v204, vcc, 0x1800000, v26
	s_nop 1
	v_addc_co_u32_e32 v205, vcc, 0, v27, vcc
	global_load_dwordx2 v[204:205], v[204:205], off
	v_add_co_u32_e32 v206, vcc, 0x1a00000, v26
	s_nop 1
	v_addc_co_u32_e32 v207, vcc, 0, v27, vcc
	global_load_dwordx2 v[206:207], v[206:207], off
	v_add_co_u32_e32 v208, vcc, 0x1c00000, v26
	s_nop 1
	v_addc_co_u32_e32 v209, vcc, 0, v27, vcc
	global_load_dwordx2 v[208:209], v[208:209], off
	v_add_co_u32_e32 v210, vcc, 0x1e00000, v26
	s_nop 1
	v_addc_co_u32_e32 v211, vcc, 0, v27, vcc
	global_load_dwordx2 v[210:211], v[210:211], off
	s_mov_b32 s0, 0x200000
	v_add_co_u32_e32 v36, vcc, s0, v26
	global_load_dwordx2 v[12:13], v[26:27], off
	s_nop 0
	v_addc_co_u32_e32 v37, vcc, 0, v27, vcc
	global_load_dwordx2 v[36:37], v[36:37], off
	v_lshl_add_u64 v[10:11], s[12:13], 1, v[24:25]
	v_readlane_b32 s10, v252, 31
	v_readlane_b32 s11, v252, 32
	s_waitcnt vmcnt(1)
	v_cvt_f32_f16_sdwa v31, v12 dst_sel:DWORD dst_unused:UNUSED_PAD src0_sel:WORD_1
	v_cvt_f32_f16_sdwa v33, v13 dst_sel:DWORD dst_unused:UNUSED_PAD src0_sel:WORD_1
	v_cvt_f32_f16_e32 v30, v12
	v_cvt_f32_f16_e32 v32, v13
	s_waitcnt vmcnt(0)
	v_cvt_f32_f16_e32 v40, v36
	v_cvt_f32_f16_sdwa v41, v36 dst_sel:DWORD dst_unused:UNUSED_PAD src0_sel:WORD_1
	v_cvt_f32_f16_e32 v38, v37
	v_cvt_f32_f16_sdwa v39, v37 dst_sel:DWORD dst_unused:UNUSED_PAD src0_sel:WORD_1
	v_pk_add_f32 v[12:13], v[32:33], 0 op_sel_hi:[1,0]
	v_pk_add_f32 v[32:33], v[30:31], 0 op_sel_hi:[1,0]
	global_load_dwordx2 v[30:31], v[10:11], off
	v_pk_add_f32 v[36:37], v[32:33], v[40:41]
	v_add_co_u32_e32 v32, vcc, s0, v10
	s_mov_b32 s0, 0x400000
	s_nop 0
	v_addc_co_u32_e32 v33, vcc, 0, v11, vcc
	v_pk_add_f32 v[12:13], v[12:13], v[38:39]
	v_add_co_u32_e32 v38, vcc, s0, v26
	global_load_dwordx2 v[32:33], v[32:33], off
	s_nop 0
	v_addc_co_u32_e32 v39, vcc, 0, v27, vcc
	v_mov_b32_e32 v38, v184
	v_mov_b32_e32 v39, v185
	v_cvt_f32_f16_e32 v40, v38
	v_cvt_f32_f16_sdwa v41, v38 dst_sel:DWORD dst_unused:UNUSED_PAD src0_sel:WORD_1
	v_cvt_f32_f16_e32 v38, v39
	v_cvt_f32_f16_sdwa v39, v39 dst_sel:DWORD dst_unused:UNUSED_PAD src0_sel:WORD_1
	v_pk_add_f32 v[12:13], v[12:13], v[38:39]
	v_pk_add_f32 v[38:39], v[36:37], v[40:41]
	v_add_co_u32_e32 v36, vcc, s0, v10
	s_mov_b32 s0, 0x600000
	s_nop 0
	v_addc_co_u32_e32 v37, vcc, 0, v11, vcc
	v_add_co_u32_e32 v40, vcc, s0, v26
	global_load_dwordx2 v[36:37], v[36:37], off
	s_nop 0
	v_addc_co_u32_e32 v41, vcc, 0, v27, vcc
	v_mov_b32_e32 v40, v186
	v_mov_b32_e32 v41, v187
	v_cvt_f32_f16_e32 v44, v40
	v_cvt_f32_f16_sdwa v45, v40 dst_sel:DWORD dst_unused:UNUSED_PAD src0_sel:WORD_1
	v_cvt_f32_f16_e32 v42, v41
	v_cvt_f32_f16_sdwa v43, v41 dst_sel:DWORD dst_unused:UNUSED_PAD src0_sel:WORD_1
	v_pk_add_f32 v[40:41], v[38:39], v[44:45]
	v_add_co_u32_e32 v38, vcc, s0, v10
	s_mov_b32 s0, 0x800000
	s_nop 0
	v_addc_co_u32_e32 v39, vcc, 0, v11, vcc
	v_pk_add_f32 v[12:13], v[12:13], v[42:43]
	v_add_co_u32_e32 v42, vcc, s0, v26
	global_load_dwordx2 v[38:39], v[38:39], off
	s_nop 0
	v_addc_co_u32_e32 v43, vcc, 0, v27, vcc
	v_mov_b32_e32 v42, v188
	v_mov_b32_e32 v43, v189
	v_cvt_f32_f16_e32 v44, v42
	v_cvt_f32_f16_sdwa v45, v42 dst_sel:DWORD dst_unused:UNUSED_PAD src0_sel:WORD_1
	v_cvt_f32_f16_e32 v42, v43
	v_cvt_f32_f16_sdwa v43, v43 dst_sel:DWORD dst_unused:UNUSED_PAD src0_sel:WORD_1
	v_pk_add_f32 v[12:13], v[12:13], v[42:43]
	v_pk_add_f32 v[42:43], v[40:41], v[44:45]
	v_add_co_u32_e32 v40, vcc, s0, v10
	s_mov_b32 s0, 0xa00000
	s_nop 0
	v_addc_co_u32_e32 v41, vcc, 0, v11, vcc
	v_add_co_u32_e32 v44, vcc, s0, v26
	global_load_dwordx2 v[40:41], v[40:41], off
	s_nop 0
	v_addc_co_u32_e32 v45, vcc, 0, v27, vcc
	v_mov_b32_e32 v44, v190
	v_mov_b32_e32 v45, v191
	v_cvt_f32_f16_e32 v48, v44
	v_cvt_f32_f16_sdwa v49, v44 dst_sel:DWORD dst_unused:UNUSED_PAD src0_sel:WORD_1
	v_cvt_f32_f16_e32 v46, v45
	v_cvt_f32_f16_sdwa v47, v45 dst_sel:DWORD dst_unused:UNUSED_PAD src0_sel:WORD_1
	v_pk_add_f32 v[44:45], v[42:43], v[48:49]
	v_add_co_u32_e32 v42, vcc, s0, v10
	s_mov_b32 s0, 0xc00000
	s_nop 0
	v_addc_co_u32_e32 v43, vcc, 0, v11, vcc
	v_pk_add_f32 v[12:13], v[12:13], v[46:47]
	v_add_co_u32_e32 v46, vcc, s0, v26
	global_load_dwordx2 v[42:43], v[42:43], off
	s_nop 0
	v_addc_co_u32_e32 v47, vcc, 0, v27, vcc
	v_mov_b32_e32 v46, v192
	v_mov_b32_e32 v47, v193
	v_cvt_f32_f16_e32 v48, v46
	v_cvt_f32_f16_sdwa v49, v46 dst_sel:DWORD dst_unused:UNUSED_PAD src0_sel:WORD_1
	v_cvt_f32_f16_e32 v46, v47
	v_cvt_f32_f16_sdwa v47, v47 dst_sel:DWORD dst_unused:UNUSED_PAD src0_sel:WORD_1
	v_pk_add_f32 v[12:13], v[12:13], v[46:47]
	v_pk_add_f32 v[46:47], v[44:45], v[48:49]
	v_add_co_u32_e32 v44, vcc, s0, v10
	s_mov_b32 s0, 0xe00000
	s_nop 0
	v_addc_co_u32_e32 v45, vcc, 0, v11, vcc
	v_add_co_u32_e32 v48, vcc, s0, v26
	global_load_dwordx2 v[44:45], v[44:45], off
	s_nop 0
	v_addc_co_u32_e32 v49, vcc, 0, v27, vcc
	v_mov_b32_e32 v48, v194
	v_mov_b32_e32 v49, v195
	v_cvt_f32_f16_e32 v52, v48
	v_cvt_f32_f16_sdwa v53, v48 dst_sel:DWORD dst_unused:UNUSED_PAD src0_sel:WORD_1
	v_cvt_f32_f16_e32 v50, v49
	v_cvt_f32_f16_sdwa v51, v49 dst_sel:DWORD dst_unused:UNUSED_PAD src0_sel:WORD_1
	v_pk_add_f32 v[48:49], v[46:47], v[52:53]
	v_add_co_u32_e32 v46, vcc, s0, v10
	s_mov_b32 s0, 0x1000000
	s_nop 0
	v_addc_co_u32_e32 v47, vcc, 0, v11, vcc
	v_pk_add_f32 v[12:13], v[12:13], v[50:51]
	v_add_co_u32_e32 v50, vcc, s0, v26
	global_load_dwordx2 v[46:47], v[46:47], off
	s_nop 0
	v_addc_co_u32_e32 v51, vcc, 0, v27, vcc
	v_mov_b32_e32 v50, v196
	v_mov_b32_e32 v51, v197
	v_cvt_f32_f16_e32 v52, v50
	v_cvt_f32_f16_sdwa v53, v50 dst_sel:DWORD dst_unused:UNUSED_PAD src0_sel:WORD_1
	v_cvt_f32_f16_e32 v50, v51
	v_cvt_f32_f16_sdwa v51, v51 dst_sel:DWORD dst_unused:UNUSED_PAD src0_sel:WORD_1
	v_pk_add_f32 v[12:13], v[12:13], v[50:51]
	v_pk_add_f32 v[50:51], v[48:49], v[52:53]
	v_add_co_u32_e32 v48, vcc, s0, v10
	s_mov_b32 s0, 0x1200000
	s_nop 0
	v_addc_co_u32_e32 v49, vcc, 0, v11, vcc
	v_add_co_u32_e32 v52, vcc, s0, v26
	global_load_dwordx2 v[48:49], v[48:49], off
	s_nop 0
	v_addc_co_u32_e32 v53, vcc, 0, v27, vcc
	v_mov_b32_e32 v52, v198
	v_mov_b32_e32 v53, v199
	v_cvt_f32_f16_e32 v56, v52
	v_cvt_f32_f16_sdwa v57, v52 dst_sel:DWORD dst_unused:UNUSED_PAD src0_sel:WORD_1
	v_cvt_f32_f16_e32 v54, v53
	v_cvt_f32_f16_sdwa v55, v53 dst_sel:DWORD dst_unused:UNUSED_PAD src0_sel:WORD_1
	v_pk_add_f32 v[52:53], v[50:51], v[56:57]
	v_add_co_u32_e32 v50, vcc, s0, v10
	s_mov_b32 s0, 0x1400000
	s_nop 0
	v_addc_co_u32_e32 v51, vcc, 0, v11, vcc
	v_pk_add_f32 v[12:13], v[12:13], v[54:55]
	v_add_co_u32_e32 v54, vcc, s0, v26
	global_load_dwordx2 v[50:51], v[50:51], off
	s_nop 0
	v_addc_co_u32_e32 v55, vcc, 0, v27, vcc
	v_mov_b32_e32 v54, v200
	v_mov_b32_e32 v55, v201
	v_cvt_f32_f16_e32 v56, v54
	v_cvt_f32_f16_sdwa v57, v54 dst_sel:DWORD dst_unused:UNUSED_PAD src0_sel:WORD_1
	v_cvt_f32_f16_e32 v54, v55
	v_cvt_f32_f16_sdwa v55, v55 dst_sel:DWORD dst_unused:UNUSED_PAD src0_sel:WORD_1
	v_pk_add_f32 v[12:13], v[12:13], v[54:55]
	v_pk_add_f32 v[54:55], v[52:53], v[56:57]
	v_add_co_u32_e32 v52, vcc, s0, v10
	s_mov_b32 s0, 0x1600000
	s_nop 0
	v_addc_co_u32_e32 v53, vcc, 0, v11, vcc
	v_add_co_u32_e32 v56, vcc, s0, v26
	global_load_dwordx2 v[52:53], v[52:53], off
	s_nop 0
	v_addc_co_u32_e32 v57, vcc, 0, v27, vcc
	v_mov_b32_e32 v56, v202
	v_mov_b32_e32 v57, v203
	v_cvt_f32_f16_e32 v60, v56
	v_cvt_f32_f16_sdwa v61, v56 dst_sel:DWORD dst_unused:UNUSED_PAD src0_sel:WORD_1
	v_cvt_f32_f16_e32 v58, v57
	v_cvt_f32_f16_sdwa v59, v57 dst_sel:DWORD dst_unused:UNUSED_PAD src0_sel:WORD_1
	v_pk_add_f32 v[56:57], v[54:55], v[60:61]
	v_add_co_u32_e32 v54, vcc, s0, v10
	s_mov_b32 s0, 0x1800000
	s_nop 0
	v_addc_co_u32_e32 v55, vcc, 0, v11, vcc
	v_pk_add_f32 v[12:13], v[12:13], v[58:59]
	v_add_co_u32_e32 v58, vcc, s0, v26
	global_load_dwordx2 v[54:55], v[54:55], off
	s_nop 0
	v_addc_co_u32_e32 v59, vcc, 0, v27, vcc
	v_mov_b32_e32 v58, v204
	v_mov_b32_e32 v59, v205
	v_cvt_f32_f16_e32 v60, v58
	v_cvt_f32_f16_sdwa v61, v58 dst_sel:DWORD dst_unused:UNUSED_PAD src0_sel:WORD_1
	v_cvt_f32_f16_e32 v58, v59
	v_cvt_f32_f16_sdwa v59, v59 dst_sel:DWORD dst_unused:UNUSED_PAD src0_sel:WORD_1
	v_pk_add_f32 v[12:13], v[12:13], v[58:59]
	v_pk_add_f32 v[58:59], v[56:57], v[60:61]
	v_add_co_u32_e32 v56, vcc, s0, v10
	s_mov_b32 s0, 0x1a00000
	s_nop 0
	v_addc_co_u32_e32 v57, vcc, 0, v11, vcc
	v_add_co_u32_e32 v60, vcc, s0, v26
	global_load_dwordx2 v[56:57], v[56:57], off
	s_nop 0
	v_addc_co_u32_e32 v61, vcc, 0, v27, vcc
	v_mov_b32_e32 v60, v206
	v_mov_b32_e32 v61, v207
	v_cvt_f32_f16_e32 v64, v60
	v_cvt_f32_f16_sdwa v65, v60 dst_sel:DWORD dst_unused:UNUSED_PAD src0_sel:WORD_1
	v_cvt_f32_f16_e32 v62, v61
	v_cvt_f32_f16_sdwa v63, v61 dst_sel:DWORD dst_unused:UNUSED_PAD src0_sel:WORD_1
	v_pk_add_f32 v[60:61], v[58:59], v[64:65]
	v_add_co_u32_e32 v58, vcc, s0, v10
	s_mov_b32 s0, 0x1c00000
	s_nop 0
	v_addc_co_u32_e32 v59, vcc, 0, v11, vcc
	v_pk_add_f32 v[12:13], v[12:13], v[62:63]
	v_add_co_u32_e32 v62, vcc, s0, v26
	global_load_dwordx2 v[58:59], v[58:59], off
	s_nop 0
	v_addc_co_u32_e32 v63, vcc, 0, v27, vcc
	v_mov_b32_e32 v62, v208
	v_mov_b32_e32 v63, v209
	v_cvt_f32_f16_e32 v64, v62
	v_cvt_f32_f16_sdwa v65, v62 dst_sel:DWORD dst_unused:UNUSED_PAD src0_sel:WORD_1
	v_cvt_f32_f16_e32 v62, v63
	v_cvt_f32_f16_sdwa v63, v63 dst_sel:DWORD dst_unused:UNUSED_PAD src0_sel:WORD_1
	v_pk_add_f32 v[12:13], v[12:13], v[62:63]
	v_pk_add_f32 v[62:63], v[60:61], v[64:65]
	v_add_co_u32_e32 v60, vcc, s0, v10
	s_mov_b32 s0, 0x1e00000
	s_nop 0
	v_addc_co_u32_e32 v61, vcc, 0, v11, vcc
	v_add_co_u32_e32 v64, vcc, s0, v26
	global_load_dwordx2 v[60:61], v[60:61], off
	s_nop 0
	v_addc_co_u32_e32 v65, vcc, 0, v27, vcc
	v_mov_b32_e32 v64, v210
	v_mov_b32_e32 v65, v211
	v_add_co_u32_e32 v10, vcc, s0, v10
	s_ashr_i32 s0, s16, 4
	s_and_b32 s0, s0, -4
	s_add_i32 s0, s0, s4
	s_mul_hi_i32 s1, s0, 0xc000
	s_mul_i32 s0, s0, 0xc000
	s_add_u32 s0, s10, s0
	v_addc_co_u32_e32 v11, vcc, 0, v11, vcc
	s_addc_u32 s1, s11, s1
	s_waitcnt vmcnt(0)
	v_cvt_f32_f16_e32 v74, v64
	v_cvt_f32_f16_sdwa v75, v64 dst_sel:DWORD dst_unused:UNUSED_PAD src0_sel:WORD_1
	v_cvt_f32_f16_e32 v66, v65
	v_cvt_f32_f16_sdwa v67, v65 dst_sel:DWORD dst_unused:UNUSED_PAD src0_sel:WORD_1
	v_pk_add_f32 v[64:65], v[62:63], v[74:75]
	global_load_dwordx2 v[62:63], v[10:11], off
	v_lshl_add_u64 v[10:11], v[14:15], 4, s[0:1]
	v_add_co_u32_e32 v10, vcc, s73, v10
	v_pk_add_f32 v[66:67], v[12:13], v[66:67]
	s_nop 0
	v_addc_co_u32_e32 v11, vcc, 0, v11, vcc
	global_load_dwordx4 v[10:13], v[10:11], off
	s_add_i32 s0, s16, 0x2000
	s_ashr_i32 s1, s0, 31
	s_lshl_b64 s[0:1], s[0:1], 12
	s_and_b64 vcc, exec, s[40:41]
	s_waitcnt vmcnt(0)
	v_pk_fma_f32 v[8:9], v[66:67], v[12:13], v[8:9]
	v_pk_fma_f32 v[6:7], v[64:65], v[10:11], v[6:7]
	v_lshl_add_u64 v[10:11], v[20:21], 0, s[0:1]
	v_cvt_pk_f16_f32 v13, v8, v9
	v_cvt_pk_f16_f32 v12, v6, v7
	global_store_dwordx2 v[10:11], v[12:13], off
	s_cbranch_vccnz .LBB0_323
	v_cvt_f32_f16_sdwa v13, v31 dst_sel:DWORD dst_unused:UNUSED_PAD src0_sel:WORD_1
	v_cvt_f32_f16_e32 v12, v31
	v_cvt_f32_f16_sdwa v11, v30 dst_sel:DWORD dst_unused:UNUSED_PAD src0_sel:WORD_1
	v_cvt_f32_f16_e32 v10, v30
	v_cvt_f32_f16_sdwa v31, v33 dst_sel:DWORD dst_unused:UNUSED_PAD src0_sel:WORD_1
	v_cvt_f32_f16_e32 v30, v33
	v_pk_add_f32 v[12:13], v[12:13], 0 op_sel_hi:[1,0]
	v_cvt_f32_f16_sdwa v65, v32 dst_sel:DWORD dst_unused:UNUSED_PAD src0_sel:WORD_1
	v_cvt_f32_f16_e32 v64, v32
	v_pk_add_f32 v[12:13], v[12:13], v[30:31]
	v_cvt_f32_f16_sdwa v31, v36 dst_sel:DWORD dst_unused:UNUSED_PAD src0_sel:WORD_1
	v_cvt_f32_f16_e32 v30, v36
	v_pk_add_f32 v[10:11], v[10:11], 0 op_sel_hi:[1,0]
	v_cvt_f32_f16_sdwa v33, v37 dst_sel:DWORD dst_unused:UNUSED_PAD src0_sel:WORD_1
	v_pk_add_f32 v[10:11], v[10:11], v[64:65]
	v_cvt_f32_f16_e32 v32, v37
	v_pk_add_f32 v[10:11], v[10:11], v[30:31]
	v_cvt_f32_f16_sdwa v31, v39 dst_sel:DWORD dst_unused:UNUSED_PAD src0_sel:WORD_1
	v_cvt_f32_f16_e32 v30, v39
	v_pk_add_f32 v[12:13], v[12:13], v[32:33]
	v_cvt_f32_f16_sdwa v33, v38 dst_sel:DWORD dst_unused:UNUSED_PAD src0_sel:WORD_1
	v_cvt_f32_f16_e32 v32, v38
	v_pk_add_f32 v[12:13], v[12:13], v[30:31]
	v_cvt_f32_f16_sdwa v31, v40 dst_sel:DWORD dst_unused:UNUSED_PAD src0_sel:WORD_1
	v_cvt_f32_f16_e32 v30, v40
	v_pk_add_f32 v[10:11], v[10:11], v[32:33]
	v_cvt_f32_f16_sdwa v33, v41 dst_sel:DWORD dst_unused:UNUSED_PAD src0_sel:WORD_1
	v_cvt_f32_f16_e32 v32, v41
	v_pk_add_f32 v[10:11], v[10:11], v[30:31]
	v_cvt_f32_f16_sdwa v31, v43 dst_sel:DWORD dst_unused:UNUSED_PAD src0_sel:WORD_1
	v_cvt_f32_f16_e32 v30, v43
	v_pk_add_f32 v[12:13], v[12:13], v[32:33]
	v_cvt_f32_f16_sdwa v33, v42 dst_sel:DWORD dst_unused:UNUSED_PAD src0_sel:WORD_1
	v_cvt_f32_f16_e32 v32, v42
	v_pk_add_f32 v[12:13], v[12:13], v[30:31]
	v_cvt_f32_f16_sdwa v31, v44 dst_sel:DWORD dst_unused:UNUSED_PAD src0_sel:WORD_1
	v_cvt_f32_f16_e32 v30, v44
	v_pk_add_f32 v[10:11], v[10:11], v[32:33]
	v_cvt_f32_f16_sdwa v33, v45 dst_sel:DWORD dst_unused:UNUSED_PAD src0_sel:WORD_1
	v_cvt_f32_f16_e32 v32, v45
	v_pk_add_f32 v[10:11], v[10:11], v[30:31]
	v_cvt_f32_f16_sdwa v31, v47 dst_sel:DWORD dst_unused:UNUSED_PAD src0_sel:WORD_1
	v_cvt_f32_f16_e32 v30, v47
	v_pk_add_f32 v[12:13], v[12:13], v[32:33]
	v_cvt_f32_f16_sdwa v33, v46 dst_sel:DWORD dst_unused:UNUSED_PAD src0_sel:WORD_1
	v_cvt_f32_f16_e32 v32, v46
	v_pk_add_f32 v[12:13], v[12:13], v[30:31]
	v_cvt_f32_f16_sdwa v31, v48 dst_sel:DWORD dst_unused:UNUSED_PAD src0_sel:WORD_1
	v_cvt_f32_f16_e32 v30, v48
	v_pk_add_f32 v[10:11], v[10:11], v[32:33]
	v_cvt_f32_f16_sdwa v33, v49 dst_sel:DWORD dst_unused:UNUSED_PAD src0_sel:WORD_1
	v_cvt_f32_f16_e32 v32, v49
	v_pk_add_f32 v[10:11], v[10:11], v[30:31]
	v_cvt_f32_f16_sdwa v31, v51 dst_sel:DWORD dst_unused:UNUSED_PAD src0_sel:WORD_1
	v_cvt_f32_f16_e32 v30, v51
	v_pk_add_f32 v[12:13], v[12:13], v[32:33]
	v_cvt_f32_f16_sdwa v33, v50 dst_sel:DWORD dst_unused:UNUSED_PAD src0_sel:WORD_1
	v_cvt_f32_f16_e32 v32, v50
	v_pk_add_f32 v[12:13], v[12:13], v[30:31]
	v_cvt_f32_f16_sdwa v31, v52 dst_sel:DWORD dst_unused:UNUSED_PAD src0_sel:WORD_1
	v_cvt_f32_f16_e32 v30, v52
	v_pk_add_f32 v[10:11], v[10:11], v[32:33]
	v_cvt_f32_f16_sdwa v33, v53 dst_sel:DWORD dst_unused:UNUSED_PAD src0_sel:WORD_1
	v_cvt_f32_f16_e32 v32, v53
	v_pk_add_f32 v[10:11], v[10:11], v[30:31]
	v_cvt_f32_f16_sdwa v31, v55 dst_sel:DWORD dst_unused:UNUSED_PAD src0_sel:WORD_1
	v_cvt_f32_f16_e32 v30, v55
	v_pk_add_f32 v[12:13], v[12:13], v[32:33]
	v_cvt_f32_f16_sdwa v33, v54 dst_sel:DWORD dst_unused:UNUSED_PAD src0_sel:WORD_1
	v_cvt_f32_f16_e32 v32, v54
	v_pk_add_f32 v[12:13], v[12:13], v[30:31]
	v_cvt_f32_f16_sdwa v31, v56 dst_sel:DWORD dst_unused:UNUSED_PAD src0_sel:WORD_1
	v_cvt_f32_f16_e32 v30, v56
	v_pk_add_f32 v[10:11], v[10:11], v[32:33]
	v_cvt_f32_f16_sdwa v33, v57 dst_sel:DWORD dst_unused:UNUSED_PAD src0_sel:WORD_1
	v_cvt_f32_f16_e32 v32, v57
	v_pk_add_f32 v[10:11], v[10:11], v[30:31]
	v_cvt_f32_f16_sdwa v31, v59 dst_sel:DWORD dst_unused:UNUSED_PAD src0_sel:WORD_1
	v_cvt_f32_f16_e32 v30, v59
	v_pk_add_f32 v[12:13], v[12:13], v[32:33]
	v_cvt_f32_f16_sdwa v33, v58 dst_sel:DWORD dst_unused:UNUSED_PAD src0_sel:WORD_1
	v_cvt_f32_f16_e32 v32, v58
	v_pk_add_f32 v[12:13], v[12:13], v[30:31]
	v_cvt_f32_f16_sdwa v31, v60 dst_sel:DWORD dst_unused:UNUSED_PAD src0_sel:WORD_1
	v_cvt_f32_f16_e32 v30, v60
	s_ashr_i32 s0, s17, 4
	v_pk_add_f32 v[10:11], v[10:11], v[32:33]
	v_cvt_f32_f16_sdwa v33, v61 dst_sel:DWORD dst_unused:UNUSED_PAD src0_sel:WORD_1
	v_cvt_f32_f16_e32 v32, v61
	s_and_b32 s0, s0, -4
	v_pk_add_f32 v[10:11], v[10:11], v[30:31]
	v_cvt_f32_f16_sdwa v31, v62 dst_sel:DWORD dst_unused:UNUSED_PAD src0_sel:WORD_1
	v_cvt_f32_f16_e32 v30, v62
	s_add_i32 s0, s0, s4
	s_mul_hi_i32 s1, s0, 0xc000
	s_mul_i32 s0, s0, 0xc000
	s_add_u32 s0, s10, s0
	v_pk_add_f32 v[12:13], v[12:13], v[32:33]
	v_cvt_f32_f16_sdwa v33, v63 dst_sel:DWORD dst_unused:UNUSED_PAD src0_sel:WORD_1
	v_cvt_f32_f16_e32 v32, v63
	s_addc_u32 s1, s11, s1
	v_pk_add_f32 v[30:31], v[10:11], v[30:31]
	v_lshl_add_u64 v[10:11], v[14:15], 4, s[0:1]
	v_add_co_u32_e32 v10, vcc, s73, v10
	v_pk_add_f32 v[32:33], v[12:13], v[32:33]
	s_nop 0
	v_addc_co_u32_e32 v11, vcc, 0, v11, vcc
	global_load_dwordx4 v[10:13], v[10:11], off
	s_add_i32 s0, s17, 0x2000
	s_ashr_i32 s1, s0, 31
	s_lshl_b64 s[0:1], s[0:1], 12
	s_waitcnt vmcnt(0)
	v_pk_fma_f32 v[4:5], v[32:33], v[12:13], v[4:5]
	v_pk_fma_f32 v[2:3], v[30:31], v[10:11], v[2:3]
	v_lshl_add_u64 v[10:11], v[20:21], 0, s[0:1]
	v_cvt_pk_f16_f32 v13, v4, v5
	v_cvt_pk_f16_f32 v12, v2, v3
	global_store_dwordx2 v[10:11], v[12:13], off
